# P0 rotary-table loop: position load software-pipelined one iteration ahead (on top of batched transposes)
# baseline (speedup 1.0000x reference)
; __global__ void __launch_bounds__(512) mega_fwd(Args a_unused) {
;     ...
;         float* rope = (float*)(ws + S_ROPE); const int* pos = (const int*)kp->in[2];
;         for (int idx = bid * 512 + tid; idx < T * 32; idx += G * 512) { const int row = idx >> 5, p = idx & 31;
;             const float invf = exp2f(-(float)(2 * p) * (13.287712379549449f / 64.0f)); const float ang = (float)pos[row] * invf;
;             const double rev = (double)ang * 0.15915494309189535; const float fr_ = (float)(rev - __builtin_rint(rev));
;             rope[2 * (size_t)idx] = __builtin_amdgcn_cosf(fr_); rope[2 * (size_t)idx + 1] = __builtin_amdgcn_sinf(fr_); }
.LBB0_190:
	s_or_b64 exec, exec, s[4:5]
	s_mov_b32 s4, 0x200000
	v_cmp_gt_i32_e32 vcc, s4, v2
	s_and_saveexec_b64 s[4:5], vcc
	s_cbranch_execz .LBB0_193
	s_load_dwordx2 s[8:9], s[0:1], 0x10
	s_waitcnt lgkmcnt(0)
	v_lshl_add_u64 v[4:5], v[2:3], 3, s[16:17]
	s_mov_b64 s[10:11], 0x3200000
	s_ashr_i32 s7, s6, 31
	s_mov_b32 s18, 0x6dc9c883
	v_lshl_add_u64 v[4:5], v[4:5], 0, s[10:11]
	s_lshl_b64 s[10:11], s[6:7], 3
	v_lshl_add_u32 v1, s3, 10, v1
	s_lshl_b32 s7, s30, 10
	s_mov_b64 s[16:17], 0
	s_mov_b32 s13, 0xc2fc0000
	v_mov_b32_e32 v3, 0x42800000
	v_not_b32_e32 v6, 63
	s_mov_b32 s19, 0x3fc45f30
	s_mov_b32 s20, 0x1fffff
	v_ashrrev_i32_e32 v120, 5, v2
	v_ashrrev_i32_e32 v121, 31, v120
	v_lshl_add_u64 v[120:121], v[120:121], 2, s[8:9]
	global_load_dword v122, v[120:121], off
	s_waitcnt vmcnt(0)
.LBB0_192:
	v_and_b32_e32 v8, 62, v1
	v_cvt_f32_ubyte0_e32 v8, v8
	v_mul_f32_e32 v9, 0xbe549a78, v8
	v_cmp_gt_f32_e32 vcc, s13, v9
	v_add_u32_e32 v2, s6, v2
	v_add_u32_e32 v1, s7, v1
	v_cndmask_b32_e32 v9, 0, v3, vcc
	v_fmac_f32_e32 v9, 0xbe549a78, v8
	v_exp_f32_e32 v9, v9
	v_cndmask_b32_e32 v8, 0, v6, vcc
	v_cmp_lt_i32_e32 vcc, s20, v2
	s_or_b64 s[16:17], vcc, s[16:17]
	v_ldexp_f32 v8, v9, v8
	s_waitcnt vmcnt(1)
	v_mov_b32_e32 v7, v122
	v_ashrrev_i32_e32 v120, 5, v2
	v_min_i32_e32 v120, 0xffff, v120
	v_ashrrev_i32_e32 v121, 31, v120
	v_lshl_add_u64 v[120:121], v[120:121], 2, s[8:9]
	global_load_dword v122, v[120:121], off
	v_cvt_f32_i32_e32 v7, v7
	v_mul_f32_e32 v7, v8, v7
	v_cvt_f64_f32_e32 v[8:9], v7
	v_mul_f64 v[10:11], v[8:9], s[18:19]
	v_rndne_f64_e32 v[10:11], v[10:11]
	v_fma_f64 v[8:9], v[8:9], s[18:19], -v[10:11]
	v_cvt_f32_f64_e32 v7, v[8:9]
	v_cos_f32_e32 v8, v7
	v_sin_f32_e32 v9, v7
	global_store_dwordx2 v[4:5], v[8:9], off
	v_lshl_add_u64 v[4:5], v[4:5], 0, s[10:11]
	s_andn2_b64 exec, exec, s[16:17]
	s_cbranch_execnz .LBB0_192
